# adds: final RMSNorm and hgrn_finish loops software-pipelined (next row/token loads issued before the current compute and stores)
# speedup vs baseline: 1.0044x; 1.0044x over previous
; __device__ __forceinline__ int otid() { int t = threadIdx.x; asm volatile("" : "+v"(t)); return t; }
; __device__ __forceinline__ float siluf_(float x) { return x * __builtin_amdgcn_rcpf(1.f + __expf(-x)); }
; __device__ __forceinline__ u32x4 pack8(f32x4 a, f32x4 b) { u32x4 w; w.x = cvtpk(a[0], a[1]); w.y = cvtpk(a[2], a[3]); w.z = cvtpk(b[0], b[1]); w.w = cvtpk(b[2], b[3]); return w; }
; __device__ __forceinline__ void unpack8(u32x4 w, f32x4& a, f32x4& b) { a = (f32x4){bflo(w.x), bfhi(w.x), bflo(w.y), bfhi(w.y)}; b = (f32x4){bflo(w.z), bfhi(w.z), bflo(w.w), bfhi(w.w)}; }
; __device__ __forceinline__ void hgrn_finish(bf16_t* Pm, const float* normw) {
;     const int tid = otid(); const int lane = tid & 63, wid = tid >> 6;
;     const int gw = blockIdx.x * NWAVES + wid, NGW = gridDim.x * NWAVES;
;     f32x4 w0 = *(const f32x4*)(normw + lane * 8), w1 = *(const f32x4*)(normw + lane * 8 + 4);
;     for (int t = gw; t < T; t += NGW) {
;         bf16_t* op = Pm + (size_t)t * PW + PC_HI + lane * 8; const bf16_t* gp = Pm + (size_t)t * PW + PC_HG + lane * 8;
;         f32x4 a, b, g0, g1; unpack8(*(const u32x4*)op, a, b); unpack8(*(const u32x4*)gp, g0, g1);
;         float ss = (a[0] * a[0] + a[1] * a[1]) + (a[2] * a[2] + a[3] * a[3]) + (b[0] * b[0] + b[1] * b[1]) + (b[2] * b[2] + b[3] * b[3]);
;         ss += __shfl_xor(ss, 1); ss += __shfl_xor(ss, 2); ss += __shfl_xor(ss, 4); ss += __shfl_xor(ss, 8);
;         const float rs = __builtin_amdgcn_rsqf(ss * (1.f / 128.f) + EPS);
; #pragma unroll
;         for (int j = 0; j < 4; ++j) { a[j] = a[j] * rs * w0[j] * siluf_(g0[j]); b[j] = b[j] * rs * w1[j] * siluf_(g1[j]); }
;         *(u32x4*)op = pack8(a, b);
;     }
; }
.LBB0_813:
	s_mov_b64 s[8:9], s[90:91]
	v_mov_b32_e32 v0, v234
	s_mov_b32 s6, 0x8000
	v_mov_b32_e32 v0, v234
	s_nop 0
	v_ashrrev_i32_e32 v1, 6, v0
	v_add_u32_e32 v3, s93, v1
	v_cmp_gt_i32_e32 vcc, s6, v3
	s_and_saveexec_b64 s[6:7], vcc
	s_cbranch_execz .LBB0_816
	s_waitcnt lgkmcnt(0)
	s_load_dwordx2 s[10:11], s[8:9], 0x68
	v_readlane_b32 s12, v252, 11
	v_readlane_b32 s13, v252, 12
	s_lshl_b32 s28, s12, 9
	s_lshl_b64 s[12:13], s[28:29], 2
	v_lshlrev_b32_e32 v1, 5, v0
	s_waitcnt lgkmcnt(0)
	s_add_u32 s10, s10, s12
	v_and_b32_e32 v1, 0x7e0, v1
	s_addc_u32 s11, s11, s13
	global_load_dwordx4 v[4:7], v1, s[10:11]
	global_load_dwordx4 v[8:11], v1, s[10:11] offset:16
	v_xor_b32_e32 v1, 1, v238
	v_add_u32_e32 v15, 64, v239
	v_cmp_lt_i32_e32 vcc, v1, v15
	s_load_dwordx2 s[8:9], s[8:9], 0xd0
	v_and_b32_e32 v0, 63, v0
	v_cndmask_b32_e32 v1, v238, v1, vcc
	v_lshlrev_b32_e32 v12, 2, v1
	v_xor_b32_e32 v1, 2, v238
	v_cmp_lt_i32_e32 vcc, v1, v15
	v_lshlrev_b32_e32 v0, 4, v0
	s_nop 0
	v_cndmask_b32_e32 v1, v238, v1, vcc
	v_lshlrev_b32_e32 v13, 2, v1
	v_xor_b32_e32 v1, 4, v238
	v_cmp_lt_i32_e32 vcc, v1, v15
	s_nop 1
	v_cndmask_b32_e32 v1, v238, v1, vcc
	v_lshlrev_b32_e32 v14, 2, v1
	v_xor_b32_e32 v1, 8, v238
	v_cmp_lt_i32_e32 vcc, v1, v15
	s_nop 1
	v_cndmask_b32_e32 v1, v238, v1, vcc
	v_lshlrev_b32_e32 v15, 2, v1
	v_mov_b32_e32 v1, v2
	v_mad_i64_i32 v[0:1], s[10:11], v3, s24, v[0:1]
	s_waitcnt lgkmcnt(0)
	v_lshl_add_u64 v[0:1], s[8:9], 0, v[0:1]
	s_mov_b64 s[8:9], 0x8101500
	v_lshl_add_u64 v[0:1], v[0:1], 0, s[8:9]
	s_mov_b64 s[8:9], 0
	global_load_dwordx4 v[16:19], v[0:1], off
	global_load_dwordx4 v[20:23], v[0:1], off offset:1024
	s_waitcnt vmcnt(0)
.LBB0_815:
	v_add_u32_e32 v3, s26, v3
	s_movk_i32 s10, 0x7fff
	v_cmp_lt_i32_e32 vcc, s10, v3
	s_or_b64 s[8:9], vcc, s[8:9]
	v_lshl_add_u64 v[48:49], v[0:1], 0, s[66:67]
	s_cbranch_vccnz .Lhf_nopf
	global_load_dwordx4 v[40:43], v[48:49], off
	global_load_dwordx4 v[44:47], v[48:49], off offset:1024
.Lhf_nopf:
	v_lshlrev_b32_e32 v24, 16, v19
	v_lshlrev_b32_e32 v26, 16, v23
	v_and_b32_e32 v25, 0xffff0000, v19
	v_mul_f32_e32 v19, 0xbfb8aa3b, v26
	v_exp_f32_e32 v19, v19
	v_and_b32_e32 v27, 0xffff0000, v23
	v_lshlrev_b32_e32 v30, 16, v21
	v_and_b32_e32 v31, 0xffff0000, v21
	v_add_f32_e32 v19, 1.0, v19
	v_rcp_f32_e32 v28, v19
	v_mul_f32_e32 v19, 0xbfb8aa3b, v27
	v_exp_f32_e32 v19, v19
	v_mov_b32_e32 v34, v25
	v_add_f32_e32 v19, 1.0, v19
	v_rcp_f32_e32 v29, v19
	v_and_b32_e32 v19, 0xffff0000, v22
	v_pk_mul_f32 v[26:27], v[28:29], v[26:27]
	v_lshlrev_b32_e32 v28, 16, v17
	v_and_b32_e32 v29, 0xffff0000, v17
	v_mul_f32_e32 v17, 0xbfb8aa3b, v30
	v_exp_f32_e32 v17, v17
	v_mov_b32_e32 v37, v29
	v_mov_b32_e32 v21, v28
	v_add_f32_e32 v17, 1.0, v17
	v_rcp_f32_e32 v32, v17
	v_mul_f32_e32 v17, 0xbfb8aa3b, v31
	v_exp_f32_e32 v17, v17
	s_nop 0
	v_add_f32_e32 v17, 1.0, v17
	v_rcp_f32_e32 v33, v17
	s_nop 0
	v_pk_mul_f32 v[30:31], v[32:33], v[30:31]
	v_lshlrev_b32_e32 v32, 16, v18
	v_and_b32_e32 v33, 0xffff0000, v18
	v_lshlrev_b32_e32 v18, 16, v22
	v_mul_f32_e32 v17, 0xbfb8aa3b, v18
	v_exp_f32_e32 v17, v17
	v_mov_b32_e32 v35, v33
	v_mov_b32_e32 v22, v24
	v_mov_b32_e32 v23, v32
	v_pk_mul_f32 v[34:35], v[34:35], v[34:35]
	v_add_f32_e32 v17, 1.0, v17
	v_pk_fma_f32 v[22:23], v[22:23], v[22:23], v[34:35]
	v_rcp_f32_e32 v34, v17
	v_mul_f32_e32 v17, 0xbfb8aa3b, v19
	v_exp_f32_e32 v17, v17
	s_nop 0
	v_add_f32_e32 v17, 1.0, v17
	v_rcp_f32_e32 v35, v17
	v_and_b32_e32 v17, 0xffff0000, v20
	v_pk_mul_f32 v[18:19], v[34:35], v[18:19]
	v_and_b32_e32 v35, 0xffff0000, v16
	v_lshlrev_b32_e32 v34, 16, v16
	v_mov_b32_e32 v36, v35
	v_lshlrev_b32_e32 v16, 16, v20
	v_mov_b32_e32 v20, v34
	v_pk_mul_f32 v[36:37], v[36:37], v[36:37]
	s_nop 0
	v_pk_fma_f32 v[20:21], v[20:21], v[20:21], v[36:37]
	v_mul_f32_e32 v36, 0xbfb8aa3b, v16
	v_add_f32_e32 v20, v20, v21
	v_add_f32_e32 v20, v23, v20
	v_add_f32_e32 v20, v22, v20
	ds_bpermute_b32 v21, v12, v20
	v_mul_f32_e32 v37, 0xbfb8aa3b, v17
	v_exp_f32_e32 v36, v36
	v_exp_f32_e32 v37, v37
	s_waitcnt lgkmcnt(0)
	v_add_f32_e32 v20, v20, v21
	ds_bpermute_b32 v21, v13, v20
	v_add_f32_e32 v36, 1.0, v36
	v_add_f32_e32 v37, 1.0, v37
	v_rcp_f32_e32 v36, v36
	v_rcp_f32_e32 v37, v37
	s_waitcnt lgkmcnt(0)
	v_add_f32_e32 v20, v20, v21
	ds_bpermute_b32 v21, v14, v20
	v_pk_mul_f32 v[16:17], v[36:37], v[16:17]
	s_waitcnt lgkmcnt(0)
	v_add_f32_e32 v20, v20, v21
	ds_bpermute_b32 v21, v15, v20
	s_waitcnt lgkmcnt(0)
	v_add_f32_e32 v20, v20, v21
	v_fmamk_f32 v20, v20, 0x3c000000, v236
	v_rsq_f32_e32 v20, v20
	s_nop 0
	v_pk_mul_f32 v[22:23], v[20:21], v[34:35] op_sel_hi:[0,1]
	v_pk_mul_f32 v[22:23], v[4:5], v[22:23]
	s_nop 0
	v_pk_mul_f32 v[16:17], v[16:17], v[22:23]
	v_pk_mul_f32 v[22:23], v[20:21], v[32:33] op_sel_hi:[0,1]
	v_pk_mul_f32 v[22:23], v[8:9], v[22:23]
	v_cvt_pk_bf16_f32 v16, v16, v17
	v_pk_mul_f32 v[18:19], v[18:19], v[22:23]
	v_pk_mul_f32 v[22:23], v[20:21], v[28:29] op_sel_hi:[0,1]
	v_pk_mul_f32 v[20:21], v[20:21], v[24:25] op_sel_hi:[0,1]
	v_pk_mul_f32 v[22:23], v[6:7], v[22:23]
	v_pk_mul_f32 v[20:21], v[10:11], v[20:21]
	v_pk_mul_f32 v[22:23], v[30:31], v[22:23]
	v_pk_mul_f32 v[20:21], v[26:27], v[20:21]
	v_cvt_pk_bf16_f32 v17, v22, v23
	v_cvt_pk_bf16_f32 v18, v18, v19
	v_cvt_pk_bf16_f32 v19, v20, v21
	global_store_dwordx4 v[0:1], v[16:19], off
	v_mov_b32_e32 v0, v48
	v_mov_b32_e32 v1, v49
	s_waitcnt vmcnt(1)
	v_mov_b32_e32 v16, v40
	v_mov_b32_e32 v17, v41
	v_mov_b32_e32 v18, v42
	v_mov_b32_e32 v19, v43
	v_mov_b32_e32 v20, v44
	v_mov_b32_e32 v21, v45
	v_mov_b32_e32 v22, v46
	v_mov_b32_e32 v23, v47
	s_andn2_b64 exec, exec, s[8:9]
	s_cbranch_execnz .LBB0_815
